# plus nt hint on P3 residual loads (x is dead after this read)
# speedup vs baseline: 1.0159x; 1.0005x over previous
.LBB0_887:
	s_lshl_b32 s7, s24, 8
	v_lshl_or_b32 v146, s6, 8, v150
	v_lshlrev_b32_e32 v250, 1, v146
	v_add_u32_e32 v242, s7, v148
	v_lshl_add_u32 v220, v242, 12, v250
	v_mov_b32_e32 v221, 0
	v_lshl_add_u64 v[220:221], v[220:221], 0, s[10:11]
	global_load_dwordx4 v[188:191], v[220:221], off nt
	global_load_dwordx4 v[192:195], v[220:221], off offset:256 nt
	v_add_u32_e32 v243, s7, v151
	v_lshl_add_u32 v222, v243, 12, v250
	v_mov_b32_e32 v223, 0
	v_lshl_add_u64 v[222:223], v[222:223], 0, s[10:11]
	global_load_dwordx4 v[196:199], v[222:223], off nt
	global_load_dwordx4 v[200:203], v[222:223], off offset:256 nt
	v_add_u32_e32 v244, s7, v152
	v_lshl_add_u32 v224, v244, 12, v250
	v_mov_b32_e32 v225, 0
	v_lshl_add_u64 v[224:225], v[224:225], 0, s[10:11]
	global_load_dwordx4 v[204:207], v[224:225], off nt
	global_load_dwordx4 v[208:211], v[224:225], off offset:256 nt
	v_add_u32_e32 v245, s7, v153
	v_lshl_add_u32 v226, v245, 12, v250
	v_mov_b32_e32 v227, 0
	v_lshl_add_u64 v[226:227], v[226:227], 0, s[10:11]
	global_load_dwordx4 v[212:215], v[226:227], off nt
	global_load_dwordx4 v[216:219], v[226:227], off offset:256 nt
	s_waitcnt vmcnt(7)
	v_lshlrev_b32_e32 v228, 16, v188
	v_and_b32_e32 v229, 0xffff0000, v188
	v_lshlrev_b32_e32 v230, 16, v189
	v_and_b32_e32 v231, 0xffff0000, v189
	v_lshlrev_b32_e32 v232, 16, v190
	v_and_b32_e32 v233, 0xffff0000, v190
	v_lshlrev_b32_e32 v234, 16, v191
	v_and_b32_e32 v235, 0xffff0000, v191
	v_pk_add_f32 v[228:229], v[124:125], v[228:229]
	v_pk_add_f32 v[230:231], v[126:127], v[230:231]
	v_pk_add_f32 v[232:233], v[120:121], v[232:233]
	v_pk_add_f32 v[234:235], v[122:123], v[234:235]
	v_cvt_pk_bf16_f32 v188, v228, v229
	v_cvt_pk_bf16_f32 v189, v230, v231
	v_cvt_pk_bf16_f32 v190, v232, v233
	v_cvt_pk_bf16_f32 v191, v234, v235
	v_mul_f32_e32 v236, v229, v229
	v_mul_f32_e32 v237, v231, v231
	v_mul_f32_e32 v238, v233, v233
	v_mul_f32_e32 v239, v235, v235
	v_fmac_f32_e32 v236, v228, v228
	v_fmac_f32_e32 v237, v230, v230
	v_fmac_f32_e32 v238, v232, v232
	v_fmac_f32_e32 v239, v234, v234
	global_store_dwordx4 v[220:221], v[188:191], off
	v_add_f32_e32 v236, v236, v237
	v_add_f32_e32 v238, v238, v239
	v_add_f32_e32 v240, v236, v238
	s_waitcnt vmcnt(7)
	v_lshlrev_b32_e32 v228, 16, v192
	v_and_b32_e32 v229, 0xffff0000, v192
	v_lshlrev_b32_e32 v230, 16, v193
	v_and_b32_e32 v231, 0xffff0000, v193
	v_lshlrev_b32_e32 v232, 16, v194
	v_and_b32_e32 v233, 0xffff0000, v194
	v_lshlrev_b32_e32 v234, 16, v195
	v_and_b32_e32 v235, 0xffff0000, v195
	v_pk_add_f32 v[228:229], v[116:117], v[228:229]
	v_pk_add_f32 v[230:231], v[118:119], v[230:231]
	v_pk_add_f32 v[232:233], v[112:113], v[232:233]
	v_pk_add_f32 v[234:235], v[114:115], v[234:235]
	v_cvt_pk_bf16_f32 v192, v228, v229
	v_cvt_pk_bf16_f32 v193, v230, v231
	v_cvt_pk_bf16_f32 v194, v232, v233
	v_cvt_pk_bf16_f32 v195, v234, v235
	v_mul_f32_e32 v236, v229, v229
	v_mul_f32_e32 v237, v231, v231
	v_mul_f32_e32 v238, v233, v233
	v_mul_f32_e32 v239, v235, v235
	v_fmac_f32_e32 v236, v228, v228
	v_fmac_f32_e32 v237, v230, v230
	v_fmac_f32_e32 v238, v232, v232
	v_fmac_f32_e32 v239, v234, v234
	global_store_dwordx4 v[220:221], v[192:195], off offset:256
	v_add_f32_e32 v236, v236, v237
	v_add_f32_e32 v238, v238, v239
	v_add_f32_e32 v236, v236, v238
	v_add_f32_e32 v240, v240, v236
	v_mov_b32_e32 v241, v240
	s_nop 1
	v_permlane16_swap_b32_e32 v240, v241
	v_add_f32_e32 v240, v240, v241
	v_mov_b32_e32 v241, v240
	s_nop 1
	v_permlane32_swap_b32_e32 v240, v241
	s_and_saveexec_b64 s[24:25], s[0:1]
	v_add_f32_e32 v240, v240, v241
	ds_write_b32 v159, v240
	s_or_b64 exec, exec, s[24:25]
	v_add_u32_e32 v246, s7, v154
	v_lshl_add_u32 v220, v246, 12, v250
	v_mov_b32_e32 v221, 0
	v_lshl_add_u64 v[220:221], v[220:221], 0, s[10:11]
	global_load_dwordx4 v[188:191], v[220:221], off nt
	global_load_dwordx4 v[192:195], v[220:221], off offset:256 nt
	s_waitcnt vmcnt(9)
	v_lshlrev_b32_e32 v228, 16, v196
	v_and_b32_e32 v229, 0xffff0000, v196
	v_lshlrev_b32_e32 v230, 16, v197
	v_and_b32_e32 v231, 0xffff0000, v197
	v_lshlrev_b32_e32 v232, 16, v198
	v_and_b32_e32 v233, 0xffff0000, v198
	v_lshlrev_b32_e32 v234, 16, v199
	v_and_b32_e32 v235, 0xffff0000, v199
	v_pk_add_f32 v[228:229], v[108:109], v[228:229]
	v_pk_add_f32 v[230:231], v[110:111], v[230:231]
	v_pk_add_f32 v[232:233], v[104:105], v[232:233]
	v_pk_add_f32 v[234:235], v[106:107], v[234:235]
	v_cvt_pk_bf16_f32 v196, v228, v229
	v_cvt_pk_bf16_f32 v197, v230, v231
	v_cvt_pk_bf16_f32 v198, v232, v233
	v_cvt_pk_bf16_f32 v199, v234, v235
	v_mul_f32_e32 v236, v229, v229
	v_mul_f32_e32 v237, v231, v231
	v_mul_f32_e32 v238, v233, v233
	v_mul_f32_e32 v239, v235, v235
	v_fmac_f32_e32 v236, v228, v228
	v_fmac_f32_e32 v237, v230, v230
	v_fmac_f32_e32 v238, v232, v232
	v_fmac_f32_e32 v239, v234, v234
	global_store_dwordx4 v[222:223], v[196:199], off
	v_add_f32_e32 v236, v236, v237
	v_add_f32_e32 v238, v238, v239
	v_add_f32_e32 v240, v236, v238
	s_waitcnt vmcnt(9)
	v_lshlrev_b32_e32 v228, 16, v200
	v_and_b32_e32 v229, 0xffff0000, v200
	v_lshlrev_b32_e32 v230, 16, v201
	v_and_b32_e32 v231, 0xffff0000, v201
	v_lshlrev_b32_e32 v232, 16, v202
	v_and_b32_e32 v233, 0xffff0000, v202
	v_lshlrev_b32_e32 v234, 16, v203
	v_and_b32_e32 v235, 0xffff0000, v203
	v_pk_add_f32 v[228:229], v[100:101], v[228:229]
	v_pk_add_f32 v[230:231], v[102:103], v[230:231]
	v_pk_add_f32 v[232:233], v[96:97], v[232:233]
	v_pk_add_f32 v[234:235], v[98:99], v[234:235]
	v_cvt_pk_bf16_f32 v200, v228, v229
	v_cvt_pk_bf16_f32 v201, v230, v231
	v_cvt_pk_bf16_f32 v202, v232, v233
	v_cvt_pk_bf16_f32 v203, v234, v235
	v_mul_f32_e32 v236, v229, v229
	v_mul_f32_e32 v237, v231, v231
	v_mul_f32_e32 v238, v233, v233
	v_mul_f32_e32 v239, v235, v235
	v_fmac_f32_e32 v236, v228, v228
	v_fmac_f32_e32 v237, v230, v230
	v_fmac_f32_e32 v238, v232, v232
	v_fmac_f32_e32 v239, v234, v234
	global_store_dwordx4 v[222:223], v[200:203], off offset:256
	v_add_f32_e32 v236, v236, v237
	v_add_f32_e32 v238, v238, v239
	v_add_f32_e32 v236, v236, v238
	v_add_f32_e32 v240, v240, v236
	v_mov_b32_e32 v241, v240
	s_nop 1
	v_permlane16_swap_b32_e32 v240, v241
	v_add_f32_e32 v240, v240, v241
	v_mov_b32_e32 v241, v240
	s_nop 1
	v_permlane32_swap_b32_e32 v240, v241
	s_and_saveexec_b64 s[24:25], s[0:1]
	v_add_f32_e32 v240, v240, v241
	ds_write_b32 v161, v240
	s_or_b64 exec, exec, s[24:25]
	v_add_u32_e32 v247, s7, v155
	v_lshl_add_u32 v222, v247, 12, v250
	v_mov_b32_e32 v223, 0
	v_lshl_add_u64 v[222:223], v[222:223], 0, s[10:11]
	global_load_dwordx4 v[196:199], v[222:223], off nt
	global_load_dwordx4 v[200:203], v[222:223], off offset:256 nt
	s_waitcnt vmcnt(11)
	v_lshlrev_b32_e32 v228, 16, v204
	v_and_b32_e32 v229, 0xffff0000, v204
	v_lshlrev_b32_e32 v230, 16, v205
	v_and_b32_e32 v231, 0xffff0000, v205
	v_lshlrev_b32_e32 v232, 16, v206
	v_and_b32_e32 v233, 0xffff0000, v206
	v_lshlrev_b32_e32 v234, 16, v207
	v_and_b32_e32 v235, 0xffff0000, v207
	v_pk_add_f32 v[228:229], v[92:93], v[228:229]
	v_pk_add_f32 v[230:231], v[94:95], v[230:231]
	v_pk_add_f32 v[232:233], v[88:89], v[232:233]
	v_pk_add_f32 v[234:235], v[90:91], v[234:235]
	v_cvt_pk_bf16_f32 v204, v228, v229
	v_cvt_pk_bf16_f32 v205, v230, v231
	v_cvt_pk_bf16_f32 v206, v232, v233
	v_cvt_pk_bf16_f32 v207, v234, v235
	v_mul_f32_e32 v236, v229, v229
	v_mul_f32_e32 v237, v231, v231
	v_mul_f32_e32 v238, v233, v233
	v_mul_f32_e32 v239, v235, v235
	v_fmac_f32_e32 v236, v228, v228
	v_fmac_f32_e32 v237, v230, v230
	v_fmac_f32_e32 v238, v232, v232
	v_fmac_f32_e32 v239, v234, v234
	global_store_dwordx4 v[224:225], v[204:207], off
	v_add_f32_e32 v236, v236, v237
	v_add_f32_e32 v238, v238, v239
	v_add_f32_e32 v240, v236, v238
	s_waitcnt vmcnt(11)
	v_lshlrev_b32_e32 v228, 16, v208
	v_and_b32_e32 v229, 0xffff0000, v208
	v_lshlrev_b32_e32 v230, 16, v209
	v_and_b32_e32 v231, 0xffff0000, v209
	v_lshlrev_b32_e32 v232, 16, v210
	v_and_b32_e32 v233, 0xffff0000, v210
	v_lshlrev_b32_e32 v234, 16, v211
	v_and_b32_e32 v235, 0xffff0000, v211
	v_pk_add_f32 v[228:229], v[84:85], v[228:229]
	v_pk_add_f32 v[230:231], v[86:87], v[230:231]
	v_pk_add_f32 v[232:233], v[80:81], v[232:233]
	v_pk_add_f32 v[234:235], v[82:83], v[234:235]
	v_cvt_pk_bf16_f32 v208, v228, v229
	v_cvt_pk_bf16_f32 v209, v230, v231
	v_cvt_pk_bf16_f32 v210, v232, v233
	v_cvt_pk_bf16_f32 v211, v234, v235
	v_mul_f32_e32 v236, v229, v229
	v_mul_f32_e32 v237, v231, v231
	v_mul_f32_e32 v238, v233, v233
	v_mul_f32_e32 v239, v235, v235
	v_fmac_f32_e32 v236, v228, v228
	v_fmac_f32_e32 v237, v230, v230
	v_fmac_f32_e32 v238, v232, v232
	v_fmac_f32_e32 v239, v234, v234
	global_store_dwordx4 v[224:225], v[208:211], off offset:256
	v_add_f32_e32 v236, v236, v237
	v_add_f32_e32 v238, v238, v239
	v_add_f32_e32 v236, v236, v238
	v_add_f32_e32 v240, v240, v236
	v_mov_b32_e32 v241, v240
	s_nop 1
	v_permlane16_swap_b32_e32 v240, v241
	v_add_f32_e32 v240, v240, v241
	v_mov_b32_e32 v241, v240
	s_nop 1
	v_permlane32_swap_b32_e32 v240, v241
	s_and_saveexec_b64 s[24:25], s[0:1]
	v_add_f32_e32 v240, v240, v241
	ds_write_b32 v163, v240
	s_or_b64 exec, exec, s[24:25]
	v_add_u32_e32 v248, s7, v156
	v_lshl_add_u32 v224, v248, 12, v250
	v_mov_b32_e32 v225, 0
	v_lshl_add_u64 v[224:225], v[224:225], 0, s[10:11]
	global_load_dwordx4 v[204:207], v[224:225], off nt
	global_load_dwordx4 v[208:211], v[224:225], off offset:256 nt
	s_waitcnt vmcnt(13)
	v_lshlrev_b32_e32 v228, 16, v212
	v_and_b32_e32 v229, 0xffff0000, v212
	v_lshlrev_b32_e32 v230, 16, v213
	v_and_b32_e32 v231, 0xffff0000, v213
	v_lshlrev_b32_e32 v232, 16, v214
	v_and_b32_e32 v233, 0xffff0000, v214
	v_lshlrev_b32_e32 v234, 16, v215
	v_and_b32_e32 v235, 0xffff0000, v215
	v_pk_add_f32 v[228:229], v[76:77], v[228:229]
	v_pk_add_f32 v[230:231], v[78:79], v[230:231]
	v_pk_add_f32 v[232:233], v[72:73], v[232:233]
	v_pk_add_f32 v[234:235], v[74:75], v[234:235]
	v_cvt_pk_bf16_f32 v212, v228, v229
	v_cvt_pk_bf16_f32 v213, v230, v231
	v_cvt_pk_bf16_f32 v214, v232, v233
	v_cvt_pk_bf16_f32 v215, v234, v235
	v_mul_f32_e32 v236, v229, v229
	v_mul_f32_e32 v237, v231, v231
	v_mul_f32_e32 v238, v233, v233
	v_mul_f32_e32 v239, v235, v235
	v_fmac_f32_e32 v236, v228, v228
	v_fmac_f32_e32 v237, v230, v230
	v_fmac_f32_e32 v238, v232, v232
	v_fmac_f32_e32 v239, v234, v234
	global_store_dwordx4 v[226:227], v[212:215], off
	v_add_f32_e32 v236, v236, v237
	v_add_f32_e32 v238, v238, v239
	v_add_f32_e32 v240, v236, v238
	s_waitcnt vmcnt(13)
	v_lshlrev_b32_e32 v228, 16, v216
	v_and_b32_e32 v229, 0xffff0000, v216
	v_lshlrev_b32_e32 v230, 16, v217
	v_and_b32_e32 v231, 0xffff0000, v217
	v_lshlrev_b32_e32 v232, 16, v218
	v_and_b32_e32 v233, 0xffff0000, v218
	v_lshlrev_b32_e32 v234, 16, v219
	v_and_b32_e32 v235, 0xffff0000, v219
	v_pk_add_f32 v[228:229], v[68:69], v[228:229]
	v_pk_add_f32 v[230:231], v[70:71], v[230:231]
	v_pk_add_f32 v[232:233], v[64:65], v[232:233]
	v_pk_add_f32 v[234:235], v[66:67], v[234:235]
	v_cvt_pk_bf16_f32 v216, v228, v229
	v_cvt_pk_bf16_f32 v217, v230, v231
	v_cvt_pk_bf16_f32 v218, v232, v233
	v_cvt_pk_bf16_f32 v219, v234, v235
	v_mul_f32_e32 v236, v229, v229
	v_mul_f32_e32 v237, v231, v231
	v_mul_f32_e32 v238, v233, v233
	v_mul_f32_e32 v239, v235, v235
	v_fmac_f32_e32 v236, v228, v228
	v_fmac_f32_e32 v237, v230, v230
	v_fmac_f32_e32 v238, v232, v232
	v_fmac_f32_e32 v239, v234, v234
	global_store_dwordx4 v[226:227], v[216:219], off offset:256
	v_add_f32_e32 v236, v236, v237
	v_add_f32_e32 v238, v238, v239
	v_add_f32_e32 v236, v236, v238
	v_add_f32_e32 v240, v240, v236
	v_mov_b32_e32 v241, v240
	s_nop 1
	v_permlane16_swap_b32_e32 v240, v241
	v_add_f32_e32 v240, v240, v241
	v_mov_b32_e32 v241, v240
	s_nop 1
	v_permlane32_swap_b32_e32 v240, v241
	s_and_saveexec_b64 s[24:25], s[0:1]
	v_add_f32_e32 v240, v240, v241
	ds_write_b32 v165, v240
	s_or_b64 exec, exec, s[24:25]
	v_add_u32_e32 v249, s7, v157
	v_lshl_add_u32 v226, v249, 12, v250
	v_mov_b32_e32 v227, 0
	v_lshl_add_u64 v[226:227], v[226:227], 0, s[10:11]
	global_load_dwordx4 v[212:215], v[226:227], off nt
	global_load_dwordx4 v[216:219], v[226:227], off offset:256 nt
	s_waitcnt vmcnt(13)
	v_lshlrev_b32_e32 v228, 16, v188
	v_and_b32_e32 v229, 0xffff0000, v188
	v_lshlrev_b32_e32 v230, 16, v189
	v_and_b32_e32 v231, 0xffff0000, v189
	v_lshlrev_b32_e32 v232, 16, v190
	v_and_b32_e32 v233, 0xffff0000, v190
	v_lshlrev_b32_e32 v234, 16, v191
	v_and_b32_e32 v235, 0xffff0000, v191
	v_pk_add_f32 v[228:229], v[60:61], v[228:229]
	v_pk_add_f32 v[230:231], v[62:63], v[230:231]
	v_pk_add_f32 v[232:233], v[56:57], v[232:233]
	v_pk_add_f32 v[234:235], v[58:59], v[234:235]
	v_cvt_pk_bf16_f32 v188, v228, v229
	v_cvt_pk_bf16_f32 v189, v230, v231
	v_cvt_pk_bf16_f32 v190, v232, v233
	v_cvt_pk_bf16_f32 v191, v234, v235
	v_mul_f32_e32 v236, v229, v229
	v_mul_f32_e32 v237, v231, v231
	v_mul_f32_e32 v238, v233, v233
	v_mul_f32_e32 v239, v235, v235
	v_fmac_f32_e32 v236, v228, v228
	v_fmac_f32_e32 v237, v230, v230
	v_fmac_f32_e32 v238, v232, v232
	v_fmac_f32_e32 v239, v234, v234
	global_store_dwordx4 v[220:221], v[188:191], off
	v_add_f32_e32 v236, v236, v237
	v_add_f32_e32 v238, v238, v239
	v_add_f32_e32 v240, v236, v238
	s_waitcnt vmcnt(13)
	v_lshlrev_b32_e32 v228, 16, v192
	v_and_b32_e32 v229, 0xffff0000, v192
	v_lshlrev_b32_e32 v230, 16, v193
	v_and_b32_e32 v231, 0xffff0000, v193
	v_lshlrev_b32_e32 v232, 16, v194
	v_and_b32_e32 v233, 0xffff0000, v194
	v_lshlrev_b32_e32 v234, 16, v195
	v_and_b32_e32 v235, 0xffff0000, v195
	v_pk_add_f32 v[228:229], v[52:53], v[228:229]
	v_pk_add_f32 v[230:231], v[54:55], v[230:231]
	v_pk_add_f32 v[232:233], v[48:49], v[232:233]
	v_pk_add_f32 v[234:235], v[50:51], v[234:235]
	v_cvt_pk_bf16_f32 v192, v228, v229
	v_cvt_pk_bf16_f32 v193, v230, v231
	v_cvt_pk_bf16_f32 v194, v232, v233
	v_cvt_pk_bf16_f32 v195, v234, v235
	v_mul_f32_e32 v236, v229, v229
	v_mul_f32_e32 v237, v231, v231
	v_mul_f32_e32 v238, v233, v233
	v_mul_f32_e32 v239, v235, v235
	v_fmac_f32_e32 v236, v228, v228
	v_fmac_f32_e32 v237, v230, v230
	v_fmac_f32_e32 v238, v232, v232
	v_fmac_f32_e32 v239, v234, v234
	global_store_dwordx4 v[220:221], v[192:195], off offset:256
	v_add_f32_e32 v236, v236, v237
	v_add_f32_e32 v238, v238, v239
	v_add_f32_e32 v236, v236, v238
	v_add_f32_e32 v240, v240, v236
	v_mov_b32_e32 v241, v240
	s_nop 1
	v_permlane16_swap_b32_e32 v240, v241
	v_add_f32_e32 v240, v240, v241
	v_mov_b32_e32 v241, v240
	s_nop 1
	v_permlane32_swap_b32_e32 v240, v241
	s_and_saveexec_b64 s[24:25], s[0:1]
	v_add_f32_e32 v240, v240, v241
	ds_write_b32 v167, v240
	s_or_b64 exec, exec, s[24:25]
	s_waitcnt vmcnt(11)
	v_lshlrev_b32_e32 v228, 16, v196
	v_and_b32_e32 v229, 0xffff0000, v196
	v_lshlrev_b32_e32 v230, 16, v197
	v_and_b32_e32 v231, 0xffff0000, v197
	v_lshlrev_b32_e32 v232, 16, v198
	v_and_b32_e32 v233, 0xffff0000, v198
	v_lshlrev_b32_e32 v234, 16, v199
	v_and_b32_e32 v235, 0xffff0000, v199
	v_pk_add_f32 v[228:229], v[44:45], v[228:229]
	v_pk_add_f32 v[230:231], v[46:47], v[230:231]
	v_pk_add_f32 v[232:233], v[40:41], v[232:233]
	v_pk_add_f32 v[234:235], v[42:43], v[234:235]
	v_cvt_pk_bf16_f32 v196, v228, v229
	v_cvt_pk_bf16_f32 v197, v230, v231
	v_cvt_pk_bf16_f32 v198, v232, v233
	v_cvt_pk_bf16_f32 v199, v234, v235
	v_mul_f32_e32 v236, v229, v229
	v_mul_f32_e32 v237, v231, v231
	v_mul_f32_e32 v238, v233, v233
	v_mul_f32_e32 v239, v235, v235
	v_fmac_f32_e32 v236, v228, v228
	v_fmac_f32_e32 v237, v230, v230
	v_fmac_f32_e32 v238, v232, v232
	v_fmac_f32_e32 v239, v234, v234
	global_store_dwordx4 v[222:223], v[196:199], off
	v_add_f32_e32 v236, v236, v237
	v_add_f32_e32 v238, v238, v239
	v_add_f32_e32 v240, v236, v238
	s_waitcnt vmcnt(11)
	v_lshlrev_b32_e32 v228, 16, v200
	v_and_b32_e32 v229, 0xffff0000, v200
	v_lshlrev_b32_e32 v230, 16, v201
	v_and_b32_e32 v231, 0xffff0000, v201
	v_lshlrev_b32_e32 v232, 16, v202
	v_and_b32_e32 v233, 0xffff0000, v202
	v_lshlrev_b32_e32 v234, 16, v203
	v_and_b32_e32 v235, 0xffff0000, v203
	v_pk_add_f32 v[228:229], v[36:37], v[228:229]
	v_pk_add_f32 v[230:231], v[38:39], v[230:231]
	v_pk_add_f32 v[232:233], v[32:33], v[232:233]
	v_pk_add_f32 v[234:235], v[34:35], v[234:235]
	v_cvt_pk_bf16_f32 v200, v228, v229
	v_cvt_pk_bf16_f32 v201, v230, v231
	v_cvt_pk_bf16_f32 v202, v232, v233
	v_cvt_pk_bf16_f32 v203, v234, v235
	v_mul_f32_e32 v236, v229, v229
	v_mul_f32_e32 v237, v231, v231
	v_mul_f32_e32 v238, v233, v233
	v_mul_f32_e32 v239, v235, v235
	v_fmac_f32_e32 v236, v228, v228
	v_fmac_f32_e32 v237, v230, v230
	v_fmac_f32_e32 v238, v232, v232
	v_fmac_f32_e32 v239, v234, v234
	global_store_dwordx4 v[222:223], v[200:203], off offset:256
	v_add_f32_e32 v236, v236, v237
	v_add_f32_e32 v238, v238, v239
	v_add_f32_e32 v236, v236, v238
	v_add_f32_e32 v240, v240, v236
	v_mov_b32_e32 v241, v240
	s_nop 1
	v_permlane16_swap_b32_e32 v240, v241
	v_add_f32_e32 v240, v240, v241
	v_mov_b32_e32 v241, v240
	s_nop 1
	v_permlane32_swap_b32_e32 v240, v241
	s_and_saveexec_b64 s[24:25], s[0:1]
	v_add_f32_e32 v240, v240, v241
	ds_write_b32 v169, v240
	s_or_b64 exec, exec, s[24:25]
	s_waitcnt vmcnt(9)
	v_lshlrev_b32_e32 v228, 16, v204
	v_and_b32_e32 v229, 0xffff0000, v204
	v_lshlrev_b32_e32 v230, 16, v205
	v_and_b32_e32 v231, 0xffff0000, v205
	v_lshlrev_b32_e32 v232, 16, v206
	v_and_b32_e32 v233, 0xffff0000, v206
	v_lshlrev_b32_e32 v234, 16, v207
	v_and_b32_e32 v235, 0xffff0000, v207
	v_pk_add_f32 v[228:229], v[28:29], v[228:229]
	v_pk_add_f32 v[230:231], v[30:31], v[230:231]
	v_pk_add_f32 v[232:233], v[24:25], v[232:233]
	v_pk_add_f32 v[234:235], v[26:27], v[234:235]
	v_cvt_pk_bf16_f32 v204, v228, v229
	v_cvt_pk_bf16_f32 v205, v230, v231
	v_cvt_pk_bf16_f32 v206, v232, v233
	v_cvt_pk_bf16_f32 v207, v234, v235
	v_mul_f32_e32 v236, v229, v229
	v_mul_f32_e32 v237, v231, v231
	v_mul_f32_e32 v238, v233, v233
	v_mul_f32_e32 v239, v235, v235
	v_fmac_f32_e32 v236, v228, v228
	v_fmac_f32_e32 v237, v230, v230
	v_fmac_f32_e32 v238, v232, v232
	v_fmac_f32_e32 v239, v234, v234
	global_store_dwordx4 v[224:225], v[204:207], off
	v_add_f32_e32 v236, v236, v237
	v_add_f32_e32 v238, v238, v239
	v_add_f32_e32 v240, v236, v238
	s_waitcnt vmcnt(9)
	v_lshlrev_b32_e32 v228, 16, v208
	v_and_b32_e32 v229, 0xffff0000, v208
	v_lshlrev_b32_e32 v230, 16, v209
	v_and_b32_e32 v231, 0xffff0000, v209
	v_lshlrev_b32_e32 v232, 16, v210
	v_and_b32_e32 v233, 0xffff0000, v210
	v_lshlrev_b32_e32 v234, 16, v211
	v_and_b32_e32 v235, 0xffff0000, v211
	v_pk_add_f32 v[228:229], v[20:21], v[228:229]
	v_pk_add_f32 v[230:231], v[22:23], v[230:231]
	v_pk_add_f32 v[232:233], v[16:17], v[232:233]
	v_pk_add_f32 v[234:235], v[18:19], v[234:235]
	v_cvt_pk_bf16_f32 v208, v228, v229
	v_cvt_pk_bf16_f32 v209, v230, v231
	v_cvt_pk_bf16_f32 v210, v232, v233
	v_cvt_pk_bf16_f32 v211, v234, v235
	v_mul_f32_e32 v236, v229, v229
	v_mul_f32_e32 v237, v231, v231
	v_mul_f32_e32 v238, v233, v233
	v_mul_f32_e32 v239, v235, v235
	v_fmac_f32_e32 v236, v228, v228
	v_fmac_f32_e32 v237, v230, v230
	v_fmac_f32_e32 v238, v232, v232
	v_fmac_f32_e32 v239, v234, v234
	global_store_dwordx4 v[224:225], v[208:211], off offset:256
	v_add_f32_e32 v236, v236, v237
	v_add_f32_e32 v238, v238, v239
	v_add_f32_e32 v236, v236, v238
	v_add_f32_e32 v240, v240, v236
	v_mov_b32_e32 v241, v240
	s_nop 1
	v_permlane16_swap_b32_e32 v240, v241
	v_add_f32_e32 v240, v240, v241
	v_mov_b32_e32 v241, v240
	s_nop 1
	v_permlane32_swap_b32_e32 v240, v241
	s_and_saveexec_b64 s[24:25], s[0:1]
	v_add_f32_e32 v240, v240, v241
	ds_write_b32 v171, v240
	s_or_b64 exec, exec, s[24:25]
	s_waitcnt vmcnt(7)
	v_lshlrev_b32_e32 v228, 16, v212
	v_and_b32_e32 v229, 0xffff0000, v212
	v_lshlrev_b32_e32 v230, 16, v213
	v_and_b32_e32 v231, 0xffff0000, v213
	v_lshlrev_b32_e32 v232, 16, v214
	v_and_b32_e32 v233, 0xffff0000, v214
	v_lshlrev_b32_e32 v234, 16, v215
	v_and_b32_e32 v235, 0xffff0000, v215
	v_pk_add_f32 v[228:229], v[12:13], v[228:229]
	v_pk_add_f32 v[230:231], v[14:15], v[230:231]
	v_pk_add_f32 v[232:233], v[8:9], v[232:233]
	v_pk_add_f32 v[234:235], v[10:11], v[234:235]
	v_cvt_pk_bf16_f32 v212, v228, v229
	v_cvt_pk_bf16_f32 v213, v230, v231
	v_cvt_pk_bf16_f32 v214, v232, v233
	v_cvt_pk_bf16_f32 v215, v234, v235
	v_mul_f32_e32 v236, v229, v229
	v_mul_f32_e32 v237, v231, v231
	v_mul_f32_e32 v238, v233, v233
	v_mul_f32_e32 v239, v235, v235
	v_fmac_f32_e32 v236, v228, v228
	v_fmac_f32_e32 v237, v230, v230
	v_fmac_f32_e32 v238, v232, v232
	v_fmac_f32_e32 v239, v234, v234
	global_store_dwordx4 v[226:227], v[212:215], off
	v_add_f32_e32 v236, v236, v237
	v_add_f32_e32 v238, v238, v239
	v_add_f32_e32 v240, v236, v238
	s_waitcnt vmcnt(7)
	v_lshlrev_b32_e32 v228, 16, v216
	v_and_b32_e32 v229, 0xffff0000, v216
	v_lshlrev_b32_e32 v230, 16, v217
	v_and_b32_e32 v231, 0xffff0000, v217
	v_lshlrev_b32_e32 v232, 16, v218
	v_and_b32_e32 v233, 0xffff0000, v218
	v_lshlrev_b32_e32 v234, 16, v219
	v_and_b32_e32 v235, 0xffff0000, v219
	v_pk_add_f32 v[228:229], v[4:5], v[228:229]
	v_pk_add_f32 v[230:231], v[6:7], v[230:231]
	v_pk_add_f32 v[232:233], v[0:1], v[232:233]
	v_pk_add_f32 v[234:235], v[2:3], v[234:235]
	v_cvt_pk_bf16_f32 v216, v228, v229
	v_cvt_pk_bf16_f32 v217, v230, v231
	v_cvt_pk_bf16_f32 v218, v232, v233
	v_cvt_pk_bf16_f32 v219, v234, v235
	v_mul_f32_e32 v236, v229, v229
	v_mul_f32_e32 v237, v231, v231
	v_mul_f32_e32 v238, v233, v233
	v_mul_f32_e32 v239, v235, v235
	v_fmac_f32_e32 v236, v228, v228
	v_fmac_f32_e32 v237, v230, v230
	v_fmac_f32_e32 v238, v232, v232
	v_fmac_f32_e32 v239, v234, v234
	global_store_dwordx4 v[226:227], v[216:219], off offset:256
	v_add_f32_e32 v236, v236, v237
	v_add_f32_e32 v238, v238, v239
	v_add_f32_e32 v236, v236, v238
	v_add_f32_e32 v240, v240, v236
	v_mov_b32_e32 v241, v240
	s_nop 1
	v_permlane16_swap_b32_e32 v240, v241
	v_add_f32_e32 v240, v240, v241
	v_mov_b32_e32 v241, v240
	s_nop 1
	v_permlane32_swap_b32_e32 v240, v241
	s_and_saveexec_b64 s[24:25], s[0:1]
	v_add_f32_e32 v240, v240, v241
	ds_write_b32 v173, v240
	s_or_b64 exec, exec, s[24:25]
	v_mov_b32_e32 v144, v242
	v_mov_b32_e32 v145, 0
	v_mov_b32_e32 v112, v243
	v_mov_b32_e32 v113, 0
	v_mov_b32_e32 v96, v244
	v_mov_b32_e32 v97, 0
	v_mov_b32_e32 v80, v245
	v_mov_b32_e32 v81, 0
	v_mov_b32_e32 v64, v246
	v_mov_b32_e32 v65, 0
	v_mov_b32_e32 v48, v247
	v_mov_b32_e32 v49, 0
	v_mov_b32_e32 v32, v248
	v_mov_b32_e32 v33, 0
	v_mov_b32_e32 v16, v249
	v_mov_b32_e32 v17, 0
	s_waitcnt lgkmcnt(0)
	s_barrier
	s_and_saveexec_b64 s[24:25], s[2:3]
	s_cbranch_execz .LBB0_905
	ds_read_b128 v[0:3], v158
	ds_read_b128 v[4:7], v160
	s_ashr_i32 s7, s6, 31
	s_lshl_b64 s[6:7], s[6:7], 2
	s_add_u32 s6, s44, s6
	s_waitcnt lgkmcnt(1)
	v_add_f32_e32 v0, v0, v1
	v_add_f32_e32 v1, v2, v3
	s_addc_u32 s7, s45, s7
	v_add_f32_e32 v2, v0, v1
	v_lshlrev_b64 v[0:1], 5, v[144:145]
	v_lshl_add_u64 v[0:1], s[6:7], 0, v[0:1]
	global_store_dword v[0:1], v2, off
	s_waitcnt lgkmcnt(0)
	v_add_f32_e32 v0, v4, v5
	v_add_f32_e32 v1, v6, v7
	v_add_f32_e32 v6, v0, v1
	ds_read_b128 v[0:3], v162
	v_lshlrev_b64 v[4:5], 5, v[112:113]
	v_lshl_add_u64 v[4:5], s[6:7], 0, v[4:5]
	global_store_dword v[4:5], v6, off
	ds_read_b128 v[4:7], v164
	s_waitcnt lgkmcnt(1)
	v_add_f32_e32 v0, v0, v1
	v_add_f32_e32 v1, v2, v3
	v_add_f32_e32 v2, v0, v1
	v_lshlrev_b64 v[0:1], 5, v[96:97]
	v_lshl_add_u64 v[0:1], s[6:7], 0, v[0:1]
	global_store_dword v[0:1], v2, off
	s_waitcnt lgkmcnt(0)
	v_add_f32_e32 v0, v4, v5
	v_add_f32_e32 v1, v6, v7
	v_add_f32_e32 v6, v0, v1
	ds_read_b128 v[0:3], v166
	v_lshlrev_b64 v[4:5], 5, v[80:81]
	v_lshl_add_u64 v[4:5], s[6:7], 0, v[4:5]
	global_store_dword v[4:5], v6, off
	ds_read_b128 v[4:7], v168
	s_waitcnt lgkmcnt(1)
	v_add_f32_e32 v0, v0, v1
	v_add_f32_e32 v1, v2, v3
	v_add_f32_e32 v2, v0, v1
	v_lshlrev_b64 v[0:1], 5, v[64:65]
	v_lshl_add_u64 v[0:1], s[6:7], 0, v[0:1]
	global_store_dword v[0:1], v2, off
	s_waitcnt lgkmcnt(0)
	v_add_f32_e32 v0, v4, v5
	v_add_f32_e32 v1, v6, v7
	v_add_f32_e32 v6, v0, v1
	ds_read_b128 v[0:3], v170
	v_lshlrev_b64 v[4:5], 5, v[48:49]
	v_lshl_add_u64 v[4:5], s[6:7], 0, v[4:5]
	global_store_dword v[4:5], v6, off
	ds_read_b128 v[4:7], v172
	s_waitcnt lgkmcnt(1)
	v_add_f32_e32 v0, v0, v1
	v_add_f32_e32 v1, v2, v3
	v_add_f32_e32 v2, v0, v1
	v_lshlrev_b64 v[0:1], 5, v[32:33]
	v_lshl_add_u64 v[0:1], s[6:7], 0, v[0:1]
	global_store_dword v[0:1], v2, off
	s_waitcnt lgkmcnt(0)
	v_add_f32_e32 v0, v4, v5
	v_add_f32_e32 v1, v6, v7
	v_add_f32_e32 v2, v0, v1
	v_lshlrev_b64 v[0:1], 5, v[16:17]
	v_lshl_add_u64 v[0:1], s[6:7], 0, v[0:1]
	global_store_dword v[0:1], v2, off
